# V25 plus static priority raise for workgroups >= 256 extended to the phase-7 out-GEMM/transposes task loop
# baseline (speedup 1.0000x reference)
; DI void phase7(const Params& p, int l, unsigned char* smem) {
;   const u16* MG = (const u16*)(p.ws + W_MG);
;   const float* mod = (const float*)(p.ws + W_MOD);
;   const int ntile = 32 + 128 * 8, nextra = (l + 1 < NL) ? WIN_TT + SMALLW_TT : 0;
;   for (int t0 = blockIdx.x; t0 < ntile + nextra; t0 += gridDim.x) {
;     if (t0 >= ntile + WIN_TT) { smallw_transpose_task(p, l + 1, t0 - ntile - WIN_TT, smem); continue; }
;     if (t0 >= ntile) { win_transpose_task(p, l + 1, t0 - ntile, smem); continue; }
.LBB0_997:
	s_or_b64 exec, exec, s[2:3]
	v_readlane_b32 s2, v254, 49
	s_barrier
	s_cmp_lt_i32 s2, 3
	s_movk_i32 s3, 0xf88
	s_cselect_b32 s87, s3, 0x420
	v_readlane_b32 s3, v254, 0
	s_cmp_ge_i32 s3, s87
	s_cbranch_scc1 .LBB0_1650
	s_ashr_i32 s3, s2, 31
	s_lshl_b64 s[6:7], s[2:3], 21
	s_cmp_lt_i32 s2, 1
	s_cselect_b64 s[20:21], -1, 0
	s_cmp_gt_i32 s2, 0
	s_cselect_b64 s[4:5], -1, 0
	s_and_b64 s[8:9], s[4:5], exec
	s_mul_i32 s94, s2, 10
	s_cselect_b32 s3, 0x120, 8
	s_add_i32 s8, s2, 1
	v_writelane_b32 v254, s3, 41
	s_add_i32 s3, s94, 2
	s_ashr_i32 s9, s8, 31
	v_writelane_b32 v254, s3, 39
	s_lshl_b64 s[12:13], s[8:9], 20
	s_lshl_b64 s[10:11], s[8:9], 17
	v_writelane_b32 v254, s12, 35
	v_writelane_b32 v255, s10, 9
	s_mul_hi_i32 s3, s8, 0x120000
	v_writelane_b32 v254, s13, 36
	v_writelane_b32 v255, s11, 10
	s_lshl_b64 s[10:11], s[8:9], 16
	s_lshl_b64 s[12:13], s[8:9], 19
	v_writelane_b32 v254, s3, 63
	s_mul_i32 s3, s8, 0x120000
	s_lshl_b64 s[56:57], s[8:9], 21
	s_mul_hi_i32 s16, s8, 0x2120000
	s_mul_i32 s51, s8, 0x2120000
	v_writelane_b32 v255, s3, 0
	s_mul_hi_i32 s3, s8, 0x90000
	s_mul_i32 s14, s8, 0x90000
	s_add_u32 s8, s76, 0x1c90000
	s_addc_u32 s9, s77, 0
	s_add_u32 s15, s8, s6
	v_writelane_b32 v255, s15, 5
	s_addc_u32 s15, s9, s7
	v_writelane_b32 v255, s15, 7
	s_add_i32 s15, s94, 3
	s_add_u32 s10, s76, s10
	s_addc_u32 s11, s77, s11
	s_add_u32 s18, s10, 0x2910000
	s_addc_u32 s19, s11, 0
	v_writelane_b32 v255, s18, 11
	s_add_u32 s10, s10, 0x28d0000
	s_addc_u32 s11, s11, 0
	v_writelane_b32 v255, s19, 12
	v_writelane_b32 v254, s15, 45
	v_writelane_b32 v255, s10, 13
	s_mul_i32 s2, s2, 3
	s_nop 0
	v_writelane_b32 v255, s11, 14
	v_readlane_b32 s10, v254, 54
	s_add_u32 s10, s10, s14
	s_nop 0
	v_writelane_b32 v255, s10, 1
	v_readlane_b32 s10, v254, 55
	s_addc_u32 s3, s10, s3
	v_writelane_b32 v255, s3, 2
	s_add_u32 s3, s76, 0x7b6b800
	v_writelane_b32 v254, s3, 54
	s_addc_u32 s3, s77, 0
	v_writelane_b32 v254, s3, 55
	s_add_u32 s3, s76, s6
	s_addc_u32 s6, s77, s7
	s_add_u32 s7, s3, 0x1c90100
	v_writelane_b32 v254, s7, 47
	s_addc_u32 s7, s6, 0
	s_add_u32 s10, s3, 0x1c90080
	v_writelane_b32 v254, s7, 50
	s_addc_u32 s11, s6, 0
	v_writelane_b32 v254, s10, 43
	s_add_u32 s6, s76, 0x9b6b780
	s_addc_u32 s7, s77, 0
	v_writelane_b32 v254, s11, 44
	v_writelane_b32 v254, s6, 56
	s_nop 1
	v_writelane_b32 v254, s7, 57
	s_nop 0
	v_readlane_b32 s3, v254, 52
	s_add_u32 s3, s3, s12
	s_nop 0
	v_writelane_b32 v254, s3, 52
	s_nop 0
	v_readlane_b32 s3, v254, 53
	s_addc_u32 s3, s3, s13
	s_nop 0
	v_writelane_b32 v254, s3, 53
	s_add_u32 s3, s8, s56
	v_writelane_b32 v254, s3, 58
	s_addc_u32 s3, s9, s57
	v_writelane_b32 v254, s3, 60
	s_add_u32 s42, s76, 0x1090000
	s_addc_u32 s17, s77, 0
	s_add_i32 s43, s2, 3
	v_readlane_b32 s93, v254, 26
	v_readlane_b32 s54, v254, 25
	v_readlane_b32 s55, v254, 24
	v_readlane_b32 s90, v254, 22
	v_readlane_b32 s91, v254, 20
	v_readlane_b32 s84, v254, 18
	v_readlane_b32 s85, v254, 17
	v_readlane_b32 s52, v254, 21
	v_readlane_b32 s53, v254, 16
	v_readlane_b32 s92, v254, 15
	v_readlane_b32 s80, v254, 14
	v_readlane_b32 s2, v254, 13
	v_readlane_b32 s81, v254, 19
	v_readlane_b32 s95, v254, 0
	v_writelane_b32 v254, s20, 61
	s_mov_b32 s86, s2
	s_nop 0
	v_writelane_b32 v254, s21, 62
	v_writelane_b32 v254, s17, 59
	s_load_dwordx2 s[2:3], s[0:1], 0x0
	v_mov_b32_e32 v242, 0x12110
	s_waitcnt lgkmcnt(0)
	v_mov_b64_e32 v[240:241], s[2:3]
	s_load_dwordx2 s[2:3], s[0:1], 0x8
	ds_write_b64 v242, v[240:241]
	s_waitcnt lgkmcnt(0)
	v_mov_b64_e32 v[244:245], s[2:3]
	s_load_dwordx2 s[2:3], s[0:1], 0x120
	ds_write_b64 v242, v[244:245] offset:8
	s_waitcnt lgkmcnt(0)
	v_mov_b64_e32 v[246:247], s[2:3]
	s_nop 0
	ds_write_b64 v242, v[246:247] offset:32
	s_waitcnt lgkmcnt(0)
	s_cmpk_lt_u32 s95, 0x100
	s_cbranch_scc1 .Lprio7_skip
	s_setprio 1
.Lprio7_skip:
	s_branch .LBB0_1000
.LBB0_999:
	s_add_i32 s95, s95, s88
	s_add_i32 s81, s81, s62
	s_add_i32 s86, s86, s88
	s_add_i32 s80, s80, s66
	s_add_i32 s92, s92, s25
	s_add_i32 s53, s53, s67
	s_add_i32 s52, s52, s25
	s_add_i32 s85, s85, s25
	s_add_i32 s84, s84, s25
	s_add_i32 s91, s91, s62
	s_add_i32 s90, s90, s25
	s_add_i32 s55, s55, s67
	s_add_i32 s54, s54, s26
	s_add_i32 s93, s93, s88
	s_cmp_lt_i32 s95, s87
	s_cbranch_scc0 .LBB0_1649

; DI int TIDX() { int t = __builtin_amdgcn_workitem_id_x(); asm volatile("" : "+v"(t)); return t; }
; DI unsigned xb_xcc_id() { return (unsigned)__builtin_amdgcn_s_getreg((3 << 11) | 20) & 0xFu; }
; DI void xbar(const Params& p, unsigned* xbst) {
;   asm volatile("s_waitcnt vmcnt(0)" ::: "memory");
;   __syncthreads();
;   if (TIDX() == 0) {
;     unsigned* bar = (unsigned*)(p.ws + W_XBAR);
;     const unsigned x = xb_xcc_id();
;     __builtin_amdgcn_s_waitcnt(0);
.LBB0_1650:
	s_setprio 0
	s_waitcnt vmcnt(0)
	v_mov_b32_e32 v0, v160
	s_barrier
	s_nop 0
	v_cmp_eq_u32_e32 vcc, 0, v0
	s_and_saveexec_b64 s[2:3], vcc
	v_readlane_b32 s28, v254, 49
	s_cbranch_execnz .LBB0_1651
	s_getpc_b64 s[98:99]
